# baseline (speedup 1.0000x reference)
; #define LAS __attribute__((address_space(3)))
; DI float fexp2(float x) { return __builtin_amdgcn_exp2f(x); }
; DI f32x16 zero16() { f32x16 z; for (int i = 0; i < 16; ++i) z[i] = 0.f; return z; }
; DI void diff_attn_phase(int wv, LAS unsigned char* lds, const bf16_t* qk, const bf16_t* vt, bf16_t* ob, const float* lq1, const float* lk1, const float* lq2, const float* lk2,
;                         const float* subg, int layer_idx) {
;     ...
;         for (int t = 0; t < tmain; ++t) {
;             const int key0 = t * 64;
;             const bool more = true;
;             if (more) {
; #pragma unroll
;                 for (int i = 0; i < 2; ++i) gk[i] = *(const u32x4*)(kg + (size_t)(key0 + 64 + i * 32) * 2048); }
;             LAS unsigned char* buf = lds + (t & 1) * DA_BUF;
;             {
;                 f32x16 S0 = zero16(), S1 = zero16();
;                 {
;                     bf16x8 kf[2][4];
; #pragma unroll
;                     for (int sub = 0; sub < 2; ++sub)
; #pragma unroll
;                         for (int ks = 0; ks < 4; ++ks) kf[sub][ks] = *(const LAS bf16x8*)(buf + koff + sub * 32 * DA_KP + ks * 32);
; #pragma unroll
;                     for (int ks = 0; ks < 4; ++ks) { const bf16x8 qfr = *(const LAS bf16x8*)(qlds + ks * 1024); S0 = MFMA32(kf[0][ks], qfr, S0); S1 = MFMA32(kf[1][ks], qfr, S1); }
;                 }
;                 __builtin_amdgcn_sched_barrier(0);
; #pragma unroll
;                 for (int i = 0; i < 2; ++i) gv[i] = *(const u32x4*)(vg + (size_t)i * 64 * M_TOK + key0 + 64);
;                 bf16x8 vf[4][2];
; #pragma unroll
;                 for (int d = 0; d < 4; ++d)
; #pragma unroll
;                     for (int s2 = 0; s2 < 2; ++s2) vf[d][s2] = *(const LAS bf16x8*)(buf + voff + d * 32 * DA_VP + (16 * s2) * 2);
;                 const float base = slope2 * (float)(key0 + 8 * hh - qpos), b32 = 32.f * slope2;
; #pragma unroll
;                 for (int i = 0; i < 16; ++i) { S0[i] = S0[i] * c1 + cb[i]; S1[i] = S1[i] * c1 + cb[i]; }
;                 float mx = -INFINITY, mx1 = -INFINITY;
; #pragma unroll
;                 for (int i = 0; i < 16; ++i) { mx = fmaxf(mx, S0[i]); mx1 = fmaxf(mx1, S1[i]); }
;                 mx = fmaxf(mx, mx1 + b32) + base;
;                 mx = fmaxf(mx, __shfl_xor(mx, 32));
;                 {
;                     const float mn = fmaxf(m, mx), alpha = fexp2(m - mn); m = mn; l *= alpha;
.LBB0_424:
	s_add_i32 s14, s16, 64
	s_ashr_i32 s15, s14, 31
	s_lshl_b64 s[26:27], s[14:15], 12
	v_lshl_add_u64 v[66:67], v[114:115], 0, s[26:27]
	s_add_i32 s26, s16, 0x60
	s_ashr_i32 s27, s26, 31
	s_lshl_b64 s[26:27], s[26:27], 12
	global_load_dwordx4 v[98:101], v[66:67], off offset:2048
	v_lshl_add_u64 v[66:67], v[114:115], 0, s[26:27]
	global_load_dwordx4 v[102:105], v[66:67], off offset:2048
	s_bitcmp1_b32 s25, 0
	s_cselect_b32 s2, 0x8c00, 0
	s_add_i32 s2, s2, 0
	v_add_u32_e32 v70, s2, v153
	ds_read_b128 v[126:129], v217
	ds_read_b128 v[66:69], v70
	ds_read_b128 v[130:133], v217 offset:1024
	ds_read_b128 v[82:85], v70 offset:32
	ds_read_b128 v[134:137], v217 offset:2048
	ds_read_b128 v[86:89], v70 offset:64
	ds_read_b128 v[138:141], v217 offset:3072
	ds_read_b128 v[90:93], v70 offset:96
	ds_read_b128 v[94:97], v70 offset:8704
	ds_read_b128 v[106:109], v70 offset:8736
	ds_read_b128 v[110:113], v70 offset:8768
	ds_read_b128 v[122:125], v70 offset:8800
	v_mov_b32_e32 v121, v159
	v_mov_b32_e32 v0, v218
	s_waitcnt lgkmcnt(10)
	v_mfma_f32_32x32x16_bf16 v[66:81], v[66:69], v[126:129], 0
	s_ashr_i32 s17, s16, 31
	s_mov_b32 s3, 0x400000
	v_add_u32_e32 v118, s16, v120
	v_add_u32_e32 v191, s2, v211
	s_waitcnt lgkmcnt(8)
	v_mfma_f32_32x32x16_bf16 v[66:81], v[82:85], v[130:133], v[66:81]
	s_waitcnt lgkmcnt(6)
	v_mfma_f32_32x32x16_bf16 v[66:81], v[86:89], v[134:137], v[66:81]
	s_waitcnt lgkmcnt(4)
	v_mfma_f32_32x32x16_bf16 v[66:81], v[90:93], v[138:141], v[66:81]
	s_waitcnt lgkmcnt(3)
	v_mfma_f32_32x32x16_bf16 v[82:97], v[94:97], v[126:129], 0
	s_nop 10
	v_fmamk_f32 v127, v66, 0x3e38aa3b, v192
	v_max_f32_e32 v66, 0xff800000, v127
	v_fmamk_f32 v129, v69, 0x3e38aa3b, v189
	v_fmamk_f32 v159, v74, 0x3e38aa3b, v182
	v_fmamk_f32 v193, v75, 0x3e38aa3b, v183
	v_fmamk_f32 v196, v76, 0x3e38aa3b, v180
	v_cvt_f32_i32_e32 v126, v118
	s_waitcnt lgkmcnt(2)
	v_mfma_f32_32x32x16_bf16 v[82:97], v[106:109], v[130:133], v[82:97]
	v_lshl_add_u64 v[106:107], s[16:17], 1, v[116:117]
	v_add_co_u32_e32 v108, vcc, s3, v106
	v_fmamk_f32 v131, v70, 0x3e38aa3b, v186
	s_nop 0
	v_addc_co_u32_e32 v109, vcc, 0, v107, vcc
	v_fmamk_f32 v133, v71, 0x3e38aa3b, v187
	s_waitcnt lgkmcnt(1)
	v_mfma_f32_32x32x16_bf16 v[82:97], v[110:113], v[134:137], v[82:97]
	global_load_dwordx4 v[110:113], v[106:107], off offset:128
	s_nop 0
	global_load_dwordx4 v[106:109], v[108:109], off offset:128
	v_fmamk_f32 v135, v72, 0x3e38aa3b, v184
	v_fmamk_f32 v137, v73, 0x3e38aa3b, v185
	v_fmamk_f32 v199, v77, 0x3e38aa3b, v181
	v_fmamk_f32 v200, v78, 0x3e38aa3b, v178
	v_fmamk_f32 v204, v79, 0x3e38aa3b, v179
	v_fmamk_f32 v207, v80, 0x3e38aa3b, v176
	s_waitcnt lgkmcnt(0)
	v_mfma_f32_32x32x16_bf16 v[82:97], v[122:125], v[138:141], v[82:97]
	v_fmamk_f32 v123, v67, 0x3e38aa3b, v160
	v_fmamk_f32 v125, v68, 0x3e38aa3b, v188
	v_max3_f32 v66, v66, v123, v125
	v_max3_f32 v66, v66, v129, v131
	v_max3_f32 v66, v66, v133, v135
	v_max3_f32 v66, v66, v137, v159
	v_max3_f32 v66, v66, v193, v196
	s_nop 4
	v_fmamk_f32 v122, v82, 0x3e38aa3b, v192
	v_fmamk_f32 v124, v83, 0x3e38aa3b, v160
	v_fmamk_f32 v128, v84, 0x3e38aa3b, v188
	v_fmamk_f32 v130, v85, 0x3e38aa3b, v189
	v_max3_f32 v67, v122, s54, v124
	v_fmamk_f32 v132, v86, 0x3e38aa3b, v186
	v_fmamk_f32 v134, v87, 0x3e38aa3b, v187
	v_max3_f32 v67, v67, v128, v130
	v_fmamk_f32 v136, v88, 0x3e38aa3b, v184
	v_fmamk_f32 v143, v89, 0x3e38aa3b, v185
	v_max3_f32 v67, v67, v132, v134
	v_fmamk_f32 v169, v90, 0x3e38aa3b, v182
	v_fmamk_f32 v195, v91, 0x3e38aa3b, v183
	v_max3_f32 v67, v67, v136, v143
	v_fmamk_f32 v198, v92, 0x3e38aa3b, v180
	v_fmamk_f32 v202, v93, 0x3e38aa3b, v181
	v_max3_f32 v67, v67, v169, v195
	v_fmamk_f32 v203, v94, 0x3e38aa3b, v178
	v_fmamk_f32 v206, v95, 0x3e38aa3b, v179
	v_max3_f32 v67, v67, v198, v202
	v_fmamk_f32 v219, v96, 0x3e38aa3b, v176
	v_fmamk_f32 v222, v97, 0x3e38aa3b, v177
	v_max3_f32 v67, v67, v203, v206
	v_max3_f32 v66, v66, v199, v200
	v_max3_f32 v67, v67, v219, v222
	v_fmamk_f32 v220, v81, 0x3e38aa3b, v177
	v_max3_f32 v66, v66, v204, v207
	v_add_f32_e32 v67, v157, v67
	v_max3_f32 v66, v66, v220, v67
	v_fmac_f32_e32 v66, v160, v126
	v_mov_b32_e32 v67, v66
	s_nop 1
	v_permlane32_swap_b32_e32 v66, v67
	ds_read_b128 v[94:97], v191 offset:17408
	ds_read_b128 v[90:93], v191 offset:17440
	ds_read_b128 v[86:89], v191 offset:22016
	ds_read_b128 v[82:85], v191 offset:22048
	s_waitcnt lgkmcnt(4)
	v_max_f32_e32 v67, v66, v67
	v_add_f32_e32 v66, 0x41000000, v0
	v_cmp_gt_f32_e64 s[26:27], v67, v66
	s_cmp_lg_u64 s[26:27], 0
	s_cbranch_scc0 .Llazy_keep
	v_max_f32_e32 v218, v0, v67
	v_sub_f32_e32 v0, v0, v218
	v_exp_f32_e32 v118, v0
	s_branch .Llazy_join
.Llazy_keep:
	v_mov_b32_e32 v118, 1.0
; DI float fexp2(float x) { return __builtin_amdgcn_exp2f(x); }
; DI void diff_attn_phase(int wv, LAS unsigned char* lds, const bf16_t* qk, const bf16_t* vt, bf16_t* ob, const float* lq1, const float* lk1, const float* lq2, const float* lk2,
;                         const float* subg, int layer_idx) {
;     ...
;                     const float mn = fmaxf(m, mx), alpha = fexp2(m - mn); m = mn; l *= alpha;
; #pragma unroll
;                     for (int d = 0; d < 4; ++d) O[d] = O[d] * alpha;
;                 }
;                 const float off = base - m, off1 = off + b32;
;                 float ps = 0.f;
; #pragma unroll
;                 for (int i = 0; i < 16; ++i) { S0[i] = fexp2(S0[i] + off); S1[i] = fexp2(S1[i] + off1); ps += S0[i] + S1[i]; }
.Llazy_join:
	v_fma_f32 v126, v160, v126, -v218
	v_add_f32_e32 v223, v157, v126
	v_add_f32_e32 v0, v127, v126
	v_exp_f32_e32 v127, v0
	v_add_f32_e32 v0, v122, v223
	v_add_f32_e32 v122, v125, v126
	v_exp_f32_e32 v224, v0
	v_add_f32_e32 v0, v123, v126
	v_exp_f32_e32 v123, v122
	v_add_f32_e32 v122, v128, v223
	v_exp_f32_e32 v225, v122
	v_add_f32_e32 v122, v129, v126
	v_exp_f32_e32 v140, v122
	v_add_f32_e32 v122, v130, v223
	v_exp_f32_e32 v142, v122
	v_add_f32_e32 v122, v133, v126
	v_exp_f32_e32 v144, v122
	v_add_f32_e32 v122, v134, v223
	v_exp_f32_e32 v168, v122
	v_add_f32_e32 v122, v137, v126
	v_exp_f32_e32 v170, v122
	v_add_f32_e32 v122, v143, v223
	v_add_f32_e32 v129, v169, v223
	v_exp_f32_e32 v194, v122
	v_add_f32_e32 v122, v193, v126
	v_exp_f32_e32 v134, v129
	v_add_f32_e32 v129, v196, v126
	v_exp_f32_e32 v196, v122
	v_add_f32_e32 v122, v195, v223
	v_add_f32_e32 v125, v132, v223
	v_add_f32_e32 v130, v198, v223
	v_exp_f32_e32 v198, v122
	v_add_f32_e32 v122, v199, v126
	v_exp_f32_e32 v132, v125
	v_add_f32_e32 v125, v135, v126
	v_exp_f32_e32 v135, v130
	v_add_f32_e32 v130, v200, v126
	v_exp_f32_e32 v200, v122
	v_add_f32_e32 v122, v202, v223
	v_exp_f32_e32 v202, v122
	v_add_f32_e32 v122, v204, v126
	ds_read_b128 v[78:81], v191 offset:26624
	ds_read_b128 v[74:77], v191 offset:26656
	ds_read_b128 v[70:73], v191 offset:31232
	ds_read_b128 v[66:69], v191 offset:31264
	v_exp_f32_e32 v204, v122
	v_add_f32_e32 v122, v206, v223
	v_exp_f32_e32 v138, v0
	v_add_f32_e32 v0, v124, v223
	v_add_f32_e32 v124, v131, v126
	v_add_f32_e32 v128, v136, v223
	v_add_f32_e32 v131, v203, v223
	v_exp_f32_e32 v206, v122
	v_add_f32_e32 v122, v220, v126
	v_exp_f32_e32 v133, v128
	v_add_f32_e32 v128, v159, v126
	v_exp_f32_e32 v136, v131
	v_add_f32_e32 v131, v207, v126
	v_add_f32_e32 v137, v219, v223
	v_exp_f32_e32 v220, v122
	v_add_f32_e32 v122, v222, v223
	v_exp_f32_e32 v0, v0
	v_exp_f32_e32 v124, v124
	v_exp_f32_e32 v125, v125
	v_exp_f32_e32 v128, v128
	v_exp_f32_e32 v129, v129
	v_exp_f32_e32 v130, v130
	v_exp_f32_e32 v131, v131
	v_exp_f32_e32 v137, v137
	v_exp_f32_e32 v222, v122
	s_cmp_lg_u64 s[26:27], 0
	s_cbranch_scc0 .Llazy_norescale
	v_pk_mul_f32 v[64:65], v[64:65], v[118:119] op_sel_hi:[1,0]
	v_pk_mul_f32 v[62:63], v[62:63], v[118:119] op_sel_hi:[1,0]
	v_pk_mul_f32 v[60:61], v[60:61], v[118:119] op_sel_hi:[1,0]
	v_pk_mul_f32 v[58:59], v[58:59], v[118:119] op_sel_hi:[1,0]
	v_pk_mul_f32 v[56:57], v[56:57], v[118:119] op_sel_hi:[1,0]
	v_pk_mul_f32 v[54:55], v[54:55], v[118:119] op_sel_hi:[1,0]
	v_pk_mul_f32 v[52:53], v[52:53], v[118:119] op_sel_hi:[1,0]
	v_pk_mul_f32 v[50:51], v[50:51], v[118:119] op_sel_hi:[1,0]
	v_pk_mul_f32 v[48:49], v[48:49], v[118:119] op_sel_hi:[1,0]
	v_pk_mul_f32 v[46:47], v[46:47], v[118:119] op_sel_hi:[1,0]
	v_pk_mul_f32 v[44:45], v[44:45], v[118:119] op_sel_hi:[1,0]
	v_pk_mul_f32 v[42:43], v[42:43], v[118:119] op_sel_hi:[1,0]
	v_pk_mul_f32 v[40:41], v[40:41], v[118:119] op_sel_hi:[1,0]
	v_pk_mul_f32 v[38:39], v[38:39], v[118:119] op_sel_hi:[1,0]
	v_pk_mul_f32 v[36:37], v[36:37], v[118:119] op_sel_hi:[1,0]
	v_pk_mul_f32 v[34:35], v[34:35], v[118:119] op_sel_hi:[1,0]
	v_pk_mul_f32 v[32:33], v[32:33], v[118:119] op_sel_hi:[1,0]
	v_pk_mul_f32 v[30:31], v[30:31], v[118:119] op_sel_hi:[1,0]
	v_pk_mul_f32 v[28:29], v[28:29], v[118:119] op_sel_hi:[1,0]
	v_pk_mul_f32 v[26:27], v[26:27], v[118:119] op_sel_hi:[1,0]
	v_pk_mul_f32 v[24:25], v[24:25], v[118:119] op_sel_hi:[1,0]
	v_pk_mul_f32 v[22:23], v[22:23], v[118:119] op_sel_hi:[1,0]
	v_pk_mul_f32 v[20:21], v[20:21], v[118:119] op_sel_hi:[1,0]
	v_pk_mul_f32 v[18:19], v[18:19], v[118:119] op_sel_hi:[1,0]
	v_pk_mul_f32 v[16:17], v[16:17], v[118:119] op_sel_hi:[1,0]
	v_pk_mul_f32 v[14:15], v[14:15], v[118:119] op_sel_hi:[1,0]
	v_pk_mul_f32 v[12:13], v[12:13], v[118:119] op_sel_hi:[1,0]
	v_pk_mul_f32 v[10:11], v[10:11], v[118:119] op_sel_hi:[1,0]
	v_pk_mul_f32 v[8:9], v[8:9], v[118:119] op_sel_hi:[1,0]
	v_pk_mul_f32 v[6:7], v[6:7], v[118:119] op_sel_hi:[1,0]
	v_pk_mul_f32 v[4:5], v[4:5], v[118:119] op_sel_hi:[1,0]
	v_pk_mul_f32 v[2:3], v[2:3], v[118:119] op_sel_hi:[1,0]
; #define LAS __attribute__((address_space(3)))
; DI float fexp2(float x) { return __builtin_amdgcn_exp2f(x); }
; #define MFMA32(a, b, c) __builtin_amdgcn_mfma_f32_32x32x16_bf16((a), (b), (c), 0, 0, 0)
; DI void diff_attn_phase(int wv, LAS unsigned char* lds, const bf16_t* qk, const bf16_t* vt, bf16_t* ob, const float* lq1, const float* lk1, const float* lq2, const float* lk2,
;                         const float* subg, int layer_idx) {
;     ...
;                 float ps = 0.f;
; #pragma unroll
;                 for (int i = 0; i < 16; ++i) { S0[i] = fexp2(S0[i] + off); S1[i] = fexp2(S1[i] + off1); ps += S0[i] + S1[i]; }
;                 l += ps;
;                 const bf16x8 p0 = pack8(S0, 0), p1 = pack8(S0, 1), p2 = pack8(S1, 0), p3 = pack8(S1, 1);
;                 __builtin_amdgcn_sched_barrier(0);
; #pragma unroll
;                 for (int d = 0; d < 4; ++d) { O[d] = MFMA32(vf[d][0], p0, O[d]); O[d] = MFMA32(vf[d][1], p1, O[d]); }
;                 __builtin_amdgcn_sched_barrier(0);
; #pragma unroll
;                 for (int d = 0; d < 4; ++d)
; #pragma unroll
;                     for (int s2 = 0; s2 < 2; ++s2) vf[d][s2] = *(const LAS bf16x8*)(buf + voff + d * 32 * DA_VP + (32 + 16 * s2) * 2);
; #pragma unroll
;                 for (int d = 0; d < 4; ++d) { O[d] = MFMA32(vf[d][0], p2, O[d]); O[d] = MFMA32(vf[d][1], p3, O[d]); }
;             }
;             if (more) {
;                 LAS unsigned char* nb = lds + ((t + 1) & 1) * DA_BUF;
; #pragma unroll
;                 for (int i = 0; i < 2; ++i) { *(LAS u32x4*)(nb + kst_off + i * 32 * DA_KP) = gk[i]; *(LAS u32x4*)(nb + vst_off + i * 64 * DA_VP) = gv[i]; } }
;             __syncthreads();
.Llazy_norescale:
	v_add_f32_e32 v139, v127, v224
	v_add_f32_e32 v141, v123, v225
	v_add_f32_e32 v145, v124, v132
	v_add_f32_e32 v171, v125, v133
	v_add_f32_e32 v197, v128, v134
	v_add_f32_e32 v201, v129, v135
	v_add_f32_e32 v205, v130, v136
	v_add_f32_e32 v221, v131, v137
	v_cvt_pk_bf16_f32 v122, v127, v138
	v_cvt_pk_bf16_f32 v123, v123, v140
	v_cvt_pk_bf16_f32 v124, v124, v144
	v_cvt_pk_bf16_f32 v125, v125, v170
	v_cvt_pk_bf16_f32 v126, v128, v196
	v_cvt_pk_bf16_f32 v127, v129, v200
	v_cvt_pk_bf16_f32 v128, v130, v204
	v_cvt_pk_bf16_f32 v129, v131, v220
	v_cvt_pk_bf16_f32 v130, v224, v0
	v_cvt_pk_bf16_f32 v131, v225, v142
	v_cvt_pk_bf16_f32 v132, v132, v168
	v_cvt_pk_bf16_f32 v133, v133, v194
	v_cvt_pk_bf16_f32 v134, v134, v198
	v_cvt_pk_bf16_f32 v135, v135, v202
	v_cvt_pk_bf16_f32 v136, v136, v206
	v_cvt_pk_bf16_f32 v137, v137, v222
	s_waitcnt lgkmcnt(5)
	v_mfma_f32_32x32x16_bf16 v[34:49], v[86:89], v[122:125], v[34:49]
	s_waitcnt lgkmcnt(4)
	v_mfma_f32_32x32x16_bf16 v[34:49], v[82:85], v[126:129], v[34:49]
	v_add_f32_e64 v82, v138, v0
	v_add_f32_e64 v83, v139, v1
	s_waitcnt lgkmcnt(3)
	v_mfma_f32_32x32x16_bf16 v[18:33], v[78:81], v[122:125], v[18:33]
	v_add_f32_e64 v78, v82, v82
	v_add_f32_e64 v79, v82, v83
	v_mov_b32_e32 v143, v79
	v_add_f32_e64 v78, v140, v142
	v_add_f32_e64 v79, v141, v143
	v_pk_add_f32 v[78:79], v[78:79], v[78:79] op_sel_hi:[0,1]
	v_mov_b32_e32 v169, v79
	v_pk_add_f32 v[78:79], v[144:145], v[168:169]
	v_mfma_f32_32x32x16_bf16 v[50:65], v[94:97], v[122:125], v[50:65]
	v_pk_add_f32 v[78:79], v[78:79], v[78:79] op_sel_hi:[0,1]
	v_mov_b32_e32 v195, v79
	s_waitcnt lgkmcnt(1)
	v_mfma_f32_32x32x16_bf16 v[2:17], v[70:73], v[122:125], v[2:17]
	v_mfma_f32_32x32x16_bf16 v[18:33], v[74:77], v[126:129], v[18:33]
	v_add_f32_e64 v74, v170, v194
	v_add_f32_e64 v75, v171, v195
	v_pk_add_f32 v[74:75], v[74:75], v[74:75] op_sel_hi:[0,1]
	v_mov_b32_e32 v199, v75
	v_pk_add_f32 v[74:75], v[196:197], v[198:199]
	s_nop 0
	v_pk_add_f32 v[74:75], v[74:75], v[74:75] op_sel_hi:[0,1]
	v_mov_b32_e32 v203, v75
	v_mfma_f32_32x32x16_bf16 v[50:65], v[90:93], v[126:129], v[50:65]
	v_add_f32_e64 v70, v200, v202
	v_add_f32_e64 v71, v201, v203
	v_pk_add_f32 v[70:71], v[70:71], v[70:71] op_sel_hi:[0,1]
	v_mov_b32_e32 v207, v71
	v_pk_add_f32 v[70:71], v[204:205], v[206:207]
	s_nop 0
	v_pk_add_f32 v[70:71], v[70:71], v[70:71] op_sel_hi:[0,1]
	s_waitcnt lgkmcnt(0)
	v_mfma_f32_32x32x16_bf16 v[2:17], v[66:69], v[126:129], v[2:17]
	v_mov_b32_e32 v223, v71
	v_add_f32_e64 v70, v220, v222
	v_add_f32_e64 v71, v221, v223
	v_add_f32_e32 v159, v70, v71
	ds_read_b128 v[66:69], v191 offset:17472
	ds_read_b128 v[70:73], v191 offset:17504
	ds_read_b128 v[78:81], v191 offset:22080
	ds_read_b128 v[82:85], v191 offset:22112
	ds_read_b128 v[86:89], v191 offset:26688
	ds_read_b128 v[90:93], v191 offset:26720
	ds_read_b128 v[94:97], v191 offset:31296
	ds_read_b128 v[74:77], v191 offset:31328
	s_add_i32 s25, s25, 1
	s_bitcmp1_b32 s25, 0
	s_cselect_b32 s2, 0x8c00, 0
	s_add_i32 s2, s2, 0
	v_add_u32_e32 v0, s2, v167
	v_add_u32_e32 v223, s2, v208
	v_fmac_f32_e32 v159, v121, v118
	s_cmp_eq_u32 s1, s25
	s_mov_b32 s16, s14
	s_waitcnt vmcnt(3)
	ds_write_b128 v0, v[98:101]
	s_waitcnt vmcnt(1)
	ds_write_b128 v223, v[110:113] offset:17408
	ds_write_b128 v0, v[102:105] offset:8704
	s_waitcnt vmcnt(0)
	ds_write_b128 v223, v[106:109] offset:26624
	s_waitcnt lgkmcnt(11)
	v_mfma_f32_32x32x16_bf16 v[50:65], v[66:69], v[130:133], v[50:65]
	s_waitcnt lgkmcnt(10)
	v_mfma_f32_32x32x16_bf16 v[50:65], v[70:73], v[134:137], v[50:65]
	s_waitcnt lgkmcnt(9)
	v_mfma_f32_32x32x16_bf16 v[34:49], v[78:81], v[130:133], v[34:49]
	s_waitcnt lgkmcnt(8)
	v_mfma_f32_32x32x16_bf16 v[34:49], v[82:85], v[134:137], v[34:49]
	s_waitcnt lgkmcnt(7)
	v_mfma_f32_32x32x16_bf16 v[18:33], v[86:89], v[130:133], v[18:33]
	s_waitcnt lgkmcnt(6)
	v_mfma_f32_32x32x16_bf16 v[18:33], v[90:93], v[134:137], v[18:33]
	s_waitcnt lgkmcnt(5)
	v_mfma_f32_32x32x16_bf16 v[2:17], v[94:97], v[130:133], v[2:17]
	s_waitcnt lgkmcnt(0)
	s_barrier
	v_mfma_f32_32x32x16_bf16 v[2:17], v[74:77], v[134:137], v[2:17]
	s_cbranch_scc0 .LBB0_424
	s_branch .LBB0_427
